# xcd barrier: generation numbers are per-instance constants (no unsigned divisions on the last arriver's path)
# speedup vs baseline: 1.0005x; 1.0005x over previous
; __device__ __forceinline__ unsigned xb_ld(unsigned* p)              { return __hip_atomic_load(p, __ATOMIC_RELAXED, __HIP_MEMORY_SCOPE_AGENT); }
; __device__ __forceinline__ unsigned xb_add(unsigned* p, unsigned v) { return __hip_atomic_fetch_add(p, v, __ATOMIC_RELAXED, __HIP_MEMORY_SCOPE_AGENT); }
; #define XB_SPIN(cond, bar) do { unsigned _sp = 0; while (cond) { __builtin_amdgcn_s_sleep(1); \
;     if ((++_sp & 255u) == 0u) { if (xb_ld(&(bar)[XB_TMO])) break; if (_sp > XB_SPIN_CAP) { atomicAdd(&(bar)[XB_TMO], 1u); break; } } } } while (0)
; __device__ __forceinline__ void xcd_barrier(const XcdBarrier& b) {
;     ...
;         unsigned nloc = b.st[0], nx = b.st[1];
;         if (nloc == 0u) { xcd_barrier_complete(bar, b.x, nloc, nx); b.st[0] = nloc; b.st[1] = nx; }
;         const unsigned old = xb_add(&bar[XB_XSUB(b.x)], 1u);
;         const unsigned gen = old / nloc;
;         if (old + 1u == (gen + 1u) * nloc) {
;     ...
;             XB_SPIN(xb_ld(&bar[XB_XGEN(b.x)]) == gen, bar);
.LBB0_127:
	s_or_b64 exec, exec, s[12:13]
	v_cvt_f32_u32_e32 v4, v2
	s_waitcnt vmcnt(0)
	buffer_inv sc1
	v_readfirstlane_b32 s4, v3
	v_mul_u32_u24_e32 v2, 1, v2
	s_nop 1
	v_add_u32_e32 v5, s4, v1
	v_add_u32_e32 v3, 1, v5
	v_mov_b32_e32 v1, 0
	v_cmp_ne_u32_e32 vcc, v3, v2
	s_and_saveexec_b64 s[4:5], vcc
	s_xor_b64 s[4:5], exec, s[4:5]
	s_cbranch_execz .LBB0_141
	s_waitcnt lgkmcnt(0)
	v_mov_b32_e32 v0, 0x2000
	global_load_dword v0, v0, s[2:3] offset:1024 sc1
	s_add_u32 s16, s2, 0x2400
	s_addc_u32 s17, s3, 0
	s_waitcnt vmcnt(0)
	v_cmp_eq_u32_e32 vcc, v0, v1
	s_and_saveexec_b64 s[12:13], vcc
	s_cbranch_execz .LBB0_140
	s_add_u32 s14, s66, 0x4200
	s_addc_u32 s15, s67, 0
	s_mov_b32 s28, 1
	s_mov_b64 s[18:19], 0
	v_mov_b32_e32 v0, 0
	s_branch .LBB0_131

; __device__ __forceinline__ unsigned xb_ld(unsigned* p)              { return __hip_atomic_load(p, __ATOMIC_RELAXED, __HIP_MEMORY_SCOPE_AGENT); }
; __device__ __forceinline__ unsigned xb_add(unsigned* p, unsigned v) { return __hip_atomic_fetch_add(p, v, __ATOMIC_RELAXED, __HIP_MEMORY_SCOPE_AGENT); }
; #define XB_SPIN(cond, bar) do { unsigned _sp = 0; while (cond) { __builtin_amdgcn_s_sleep(1); \
;     if ((++_sp & 255u) == 0u) { if (xb_ld(&(bar)[XB_TMO])) break; if (_sp > XB_SPIN_CAP) { atomicAdd(&(bar)[XB_TMO], 1u); break; } } } } while (0)
; __device__ __forceinline__ void xcd_barrier(const XcdBarrier& b) {
;     ...
;             const unsigned og = xb_add(&bar[XB_TOP], 1u);
;             const unsigned tg = og / nx;
;             if (og + 1u == (tg + 1u) * nx) xb_add(&bar[XB_TOPGEN], 1u);
;             else XB_SPIN(xb_ld(&bar[XB_TOPGEN]) == tg, bar);
.LBB0_144:
	s_or_b64 exec, exec, s[12:13]
	v_cvt_f32_u32_e32 v3, v0
	s_waitcnt vmcnt(0)
	v_readfirstlane_b32 s4, v2
	s_add_u32 s12, s66, 0x7500
	s_addc_u32 s13, s67, 0
	s_mov_b64 s[14:15], -1
	v_mul_u32_u24_e32 v0, 1, v0
	s_nop 1
	v_add_u32_e32 v1, s4, v1
	v_add_u32_e32 v4, 1, v1
	v_mov_b32_e32 v2, 0
	v_cmp_ne_u32_e32 vcc, v4, v0
	v_mov_b64_e32 v[0:1], s[12:13]
	s_cbranch_vccnz .Lxbh0_nl
	v_mov_b32_e32 v2, 1
	global_atomic_add v[0:1], v2, off
	v_subrev_co_u32_e32 v0, vcc, 0x1100, v0
	v_subbrev_co_u32_e32 v1, vcc, 0, v1, vcc
	global_atomic_add v[0:1], v2, off
	global_atomic_add v[0:1], v2, off offset:256
	global_atomic_add v[0:1], v2, off offset:512
	global_atomic_add v[0:1], v2, off offset:768
	global_atomic_add v[0:1], v2, off offset:1024
	global_atomic_add v[0:1], v2, off offset:1280
	global_atomic_add v[0:1], v2, off offset:1536
	global_atomic_add v[0:1], v2, off offset:1792
	global_atomic_add v[0:1], v2, off offset:2048
	global_atomic_add v[0:1], v2, off offset:2304
	global_atomic_add v[0:1], v2, off offset:2560
	global_atomic_add v[0:1], v2, off offset:2816
	global_atomic_add v[0:1], v2, off offset:3072
	global_atomic_add v[0:1], v2, off offset:3328
	global_atomic_add v[0:1], v2, off offset:3584
	global_atomic_add v[0:1], v2, off offset:3840
	s_mov_b64 s[4:5], exec
	s_branch .LBB0_161

; __device__ __forceinline__ unsigned xb_ld(unsigned* p)              { return __hip_atomic_load(p, __ATOMIC_RELAXED, __HIP_MEMORY_SCOPE_AGENT); }
; __device__ __forceinline__ unsigned xb_add(unsigned* p, unsigned v) { return __hip_atomic_fetch_add(p, v, __ATOMIC_RELAXED, __HIP_MEMORY_SCOPE_AGENT); }
; #define XB_SPIN(cond, bar) do { unsigned _sp = 0; while (cond) { __builtin_amdgcn_s_sleep(1); \
;     if ((++_sp & 255u) == 0u) { if (xb_ld(&(bar)[XB_TMO])) break; if (_sp > XB_SPIN_CAP) { atomicAdd(&(bar)[XB_TMO], 1u); break; } } } } while (0)
; __device__ __forceinline__ void xcd_barrier(const XcdBarrier& b) {
;     ...
;         unsigned nloc = b.st[0], nx = b.st[1];
;         if (nloc == 0u) { xcd_barrier_complete(bar, b.x, nloc, nx); b.st[0] = nloc; b.st[1] = nx; }
;         const unsigned old = xb_add(&bar[XB_XSUB(b.x)], 1u);
;         const unsigned gen = old / nloc;
;         if (old + 1u == (gen + 1u) * nloc) {
;     ...
;             XB_SPIN(xb_ld(&bar[XB_XGEN(b.x)]) == gen, bar);
.LBB0_184:
	s_or_b64 exec, exec, s[12:13]
	v_cvt_f32_u32_e32 v4, v2
	s_waitcnt vmcnt(0)
	buffer_inv sc1
	v_readfirstlane_b32 s4, v3
	v_mul_u32_u24_e32 v2, 2, v2
	s_nop 1
	v_add_u32_e32 v5, s4, v1
	v_add_u32_e32 v3, 1, v5
	v_mov_b32_e32 v1, 1
	v_cmp_ne_u32_e32 vcc, v3, v2
	s_and_saveexec_b64 s[4:5], vcc
	s_xor_b64 s[4:5], exec, s[4:5]
	s_cbranch_execz .LBB0_198
	s_waitcnt lgkmcnt(0)
	v_mov_b32_e32 v0, 0x2000
	global_load_dword v0, v0, s[2:3] offset:1024 sc1
	s_add_u32 s16, s2, 0x2400
	s_addc_u32 s17, s3, 0
	s_waitcnt vmcnt(0)
	v_cmp_eq_u32_e32 vcc, v0, v1
	s_and_saveexec_b64 s[12:13], vcc
	s_cbranch_execz .LBB0_197
	s_add_u32 s14, s66, 0x4200
	s_addc_u32 s15, s67, 0
	s_mov_b32 s28, 1
	s_mov_b64 s[18:19], 0
	v_mov_b32_e32 v0, 0
	s_branch .LBB0_188

; __device__ __forceinline__ unsigned xb_ld(unsigned* p)              { return __hip_atomic_load(p, __ATOMIC_RELAXED, __HIP_MEMORY_SCOPE_AGENT); }
; __device__ __forceinline__ unsigned xb_add(unsigned* p, unsigned v) { return __hip_atomic_fetch_add(p, v, __ATOMIC_RELAXED, __HIP_MEMORY_SCOPE_AGENT); }
; #define XB_SPIN(cond, bar) do { unsigned _sp = 0; while (cond) { __builtin_amdgcn_s_sleep(1); \
;     if ((++_sp & 255u) == 0u) { if (xb_ld(&(bar)[XB_TMO])) break; if (_sp > XB_SPIN_CAP) { atomicAdd(&(bar)[XB_TMO], 1u); break; } } } } while (0)
; __device__ __forceinline__ void xcd_barrier(const XcdBarrier& b) {
;     ...
;             const unsigned og = xb_add(&bar[XB_TOP], 1u);
;             const unsigned tg = og / nx;
;             if (og + 1u == (tg + 1u) * nx) xb_add(&bar[XB_TOPGEN], 1u);
;             else XB_SPIN(xb_ld(&bar[XB_TOPGEN]) == tg, bar);
.LBB0_201:
	s_or_b64 exec, exec, s[12:13]
	v_cvt_f32_u32_e32 v3, v0
	s_waitcnt vmcnt(0)
	v_readfirstlane_b32 s4, v2
	s_add_u32 s12, s66, 0x7500
	s_addc_u32 s13, s67, 0
	s_mov_b64 s[14:15], -1
	v_mul_u32_u24_e32 v0, 2, v0
	s_nop 1
	v_add_u32_e32 v1, s4, v1
	v_add_u32_e32 v4, 1, v1
	v_mov_b32_e32 v2, 1
	v_cmp_ne_u32_e32 vcc, v4, v0
	v_mov_b64_e32 v[0:1], s[12:13]
	s_cbranch_vccnz .Lxbh1_nl
	v_mov_b32_e32 v2, 1
	global_atomic_add v[0:1], v2, off
	v_subrev_co_u32_e32 v0, vcc, 0x1100, v0
	v_subbrev_co_u32_e32 v1, vcc, 0, v1, vcc
	global_atomic_add v[0:1], v2, off
	global_atomic_add v[0:1], v2, off offset:256
	global_atomic_add v[0:1], v2, off offset:512
	global_atomic_add v[0:1], v2, off offset:768
	global_atomic_add v[0:1], v2, off offset:1024
	global_atomic_add v[0:1], v2, off offset:1280
	global_atomic_add v[0:1], v2, off offset:1536
	global_atomic_add v[0:1], v2, off offset:1792
	global_atomic_add v[0:1], v2, off offset:2048
	global_atomic_add v[0:1], v2, off offset:2304
	global_atomic_add v[0:1], v2, off offset:2560
	global_atomic_add v[0:1], v2, off offset:2816
	global_atomic_add v[0:1], v2, off offset:3072
	global_atomic_add v[0:1], v2, off offset:3328
	global_atomic_add v[0:1], v2, off offset:3584
	global_atomic_add v[0:1], v2, off offset:3840
	s_mov_b64 s[4:5], exec
	s_branch .LBB0_218

; __device__ __forceinline__ unsigned xb_ld(unsigned* p)              { return __hip_atomic_load(p, __ATOMIC_RELAXED, __HIP_MEMORY_SCOPE_AGENT); }
; __device__ __forceinline__ unsigned xb_add(unsigned* p, unsigned v) { return __hip_atomic_fetch_add(p, v, __ATOMIC_RELAXED, __HIP_MEMORY_SCOPE_AGENT); }
; #define XB_SPIN(cond, bar) do { unsigned _sp = 0; while (cond) { __builtin_amdgcn_s_sleep(1); \
;     if ((++_sp & 255u) == 0u) { if (xb_ld(&(bar)[XB_TMO])) break; if (_sp > XB_SPIN_CAP) { atomicAdd(&(bar)[XB_TMO], 1u); break; } } } } while (0)
; __device__ __forceinline__ void xcd_barrier(const XcdBarrier& b) {
;     ...
;         unsigned nloc = b.st[0], nx = b.st[1];
;         if (nloc == 0u) { xcd_barrier_complete(bar, b.x, nloc, nx); b.st[0] = nloc; b.st[1] = nx; }
;         const unsigned old = xb_add(&bar[XB_XSUB(b.x)], 1u);
;         const unsigned gen = old / nloc;
;         if (old + 1u == (gen + 1u) * nloc) {
;     ...
;             XB_SPIN(xb_ld(&bar[XB_XGEN(b.x)]) == gen, bar);
.LBB0_988:
	s_or_b64 exec, exec, s[16:17]
	v_cvt_f32_u32_e32 v4, v2
	s_waitcnt vmcnt(0)
	buffer_inv sc1
	v_readfirstlane_b32 s10, v3
	v_mul_u32_u24_e32 v2, 3, v2
	s_nop 1
	v_add_u32_e32 v5, s10, v1
	v_add_u32_e32 v3, 1, v5
	v_mov_b32_e32 v1, 2
	v_cmp_ne_u32_e32 vcc, v3, v2
	s_and_saveexec_b64 s[10:11], vcc
	s_xor_b64 s[10:11], exec, s[10:11]
	s_cbranch_execz .LBB0_1002
	s_waitcnt lgkmcnt(0)
	v_mov_b32_e32 v0, 0x2000
	global_load_dword v0, v0, s[4:5] offset:1024 sc1
	s_add_u32 s20, s4, 0x2400
	s_addc_u32 s21, s5, 0
	s_waitcnt vmcnt(0)
	v_cmp_eq_u32_e32 vcc, v0, v1
	s_and_saveexec_b64 s[16:17], vcc
	s_cbranch_execz .LBB0_1001
	s_add_u32 s18, s66, 0x4200
	s_addc_u32 s19, s67, 0
	s_mov_b32 s33, 1
	s_mov_b64 s[22:23], 0
	v_mov_b32_e32 v0, 0
	s_branch .LBB0_992

; __device__ __forceinline__ unsigned xb_ld(unsigned* p)              { return __hip_atomic_load(p, __ATOMIC_RELAXED, __HIP_MEMORY_SCOPE_AGENT); }
; __device__ __forceinline__ unsigned xb_add(unsigned* p, unsigned v) { return __hip_atomic_fetch_add(p, v, __ATOMIC_RELAXED, __HIP_MEMORY_SCOPE_AGENT); }
; #define XB_SPIN(cond, bar) do { unsigned _sp = 0; while (cond) { __builtin_amdgcn_s_sleep(1); \
;     if ((++_sp & 255u) == 0u) { if (xb_ld(&(bar)[XB_TMO])) break; if (_sp > XB_SPIN_CAP) { atomicAdd(&(bar)[XB_TMO], 1u); break; } } } } while (0)
; __device__ __forceinline__ void xcd_barrier(const XcdBarrier& b) {
;     ...
;             const unsigned og = xb_add(&bar[XB_TOP], 1u);
;             const unsigned tg = og / nx;
;             if (og + 1u == (tg + 1u) * nx) xb_add(&bar[XB_TOPGEN], 1u);
;             else XB_SPIN(xb_ld(&bar[XB_TOPGEN]) == tg, bar);
.LBB0_1005:
	s_or_b64 exec, exec, s[16:17]
	v_cvt_f32_u32_e32 v3, v0
	s_waitcnt vmcnt(0)
	v_readfirstlane_b32 s10, v2
	s_add_u32 s16, s66, 0x7500
	s_addc_u32 s17, s67, 0
	s_mov_b64 s[18:19], -1
	v_mul_u32_u24_e32 v0, 3, v0
	s_nop 1
	v_add_u32_e32 v1, s10, v1
	v_add_u32_e32 v4, 1, v1
	v_mov_b32_e32 v2, 2
	v_cmp_ne_u32_e32 vcc, v4, v0
	v_mov_b64_e32 v[0:1], s[16:17]
	s_cbranch_vccnz .Lxbh2_nl
	v_mov_b32_e32 v2, 1
	global_atomic_add v[0:1], v2, off
	v_subrev_co_u32_e32 v0, vcc, 0x1100, v0
	v_subbrev_co_u32_e32 v1, vcc, 0, v1, vcc
	global_atomic_add v[0:1], v2, off
	global_atomic_add v[0:1], v2, off offset:256
	global_atomic_add v[0:1], v2, off offset:512
	global_atomic_add v[0:1], v2, off offset:768
	global_atomic_add v[0:1], v2, off offset:1024
	global_atomic_add v[0:1], v2, off offset:1280
	global_atomic_add v[0:1], v2, off offset:1536
	global_atomic_add v[0:1], v2, off offset:1792
	global_atomic_add v[0:1], v2, off offset:2048
	global_atomic_add v[0:1], v2, off offset:2304
	global_atomic_add v[0:1], v2, off offset:2560
	global_atomic_add v[0:1], v2, off offset:2816
	global_atomic_add v[0:1], v2, off offset:3072
	global_atomic_add v[0:1], v2, off offset:3328
	global_atomic_add v[0:1], v2, off offset:3584
	global_atomic_add v[0:1], v2, off offset:3840
	s_mov_b64 s[10:11], exec
	s_branch .LBB0_1022

; __device__ __forceinline__ unsigned xb_ld(unsigned* p)              { return __hip_atomic_load(p, __ATOMIC_RELAXED, __HIP_MEMORY_SCOPE_AGENT); }
; __device__ __forceinline__ unsigned xb_add(unsigned* p, unsigned v) { return __hip_atomic_fetch_add(p, v, __ATOMIC_RELAXED, __HIP_MEMORY_SCOPE_AGENT); }
; #define XB_SPIN(cond, bar) do { unsigned _sp = 0; while (cond) { __builtin_amdgcn_s_sleep(1); \
;     if ((++_sp & 255u) == 0u) { if (xb_ld(&(bar)[XB_TMO])) break; if (_sp > XB_SPIN_CAP) { atomicAdd(&(bar)[XB_TMO], 1u); break; } } } } while (0)
; __device__ __forceinline__ void xcd_barrier(const XcdBarrier& b) {
;     ...
;         unsigned nloc = b.st[0], nx = b.st[1];
;         if (nloc == 0u) { xcd_barrier_complete(bar, b.x, nloc, nx); b.st[0] = nloc; b.st[1] = nx; }
;         const unsigned old = xb_add(&bar[XB_XSUB(b.x)], 1u);
;         const unsigned gen = old / nloc;
;         if (old + 1u == (gen + 1u) * nloc) {
;     ...
;             XB_SPIN(xb_ld(&bar[XB_XGEN(b.x)]) == gen, bar);
.LBB0_1064:
	s_or_b64 exec, exec, s[8:9]
	v_cvt_f32_u32_e32 v4, v2
	s_waitcnt vmcnt(0)
	buffer_inv sc1
	v_readfirstlane_b32 s6, v3
	v_mul_u32_u24_e32 v2, 4, v2
	s_nop 1
	v_add_u32_e32 v5, s6, v1
	v_add_u32_e32 v3, 1, v5
	v_mov_b32_e32 v1, 3
	v_cmp_ne_u32_e32 vcc, v3, v2
	s_and_saveexec_b64 s[6:7], vcc
	s_xor_b64 s[6:7], exec, s[6:7]
	s_cbranch_execz .LBB0_1078
	s_waitcnt lgkmcnt(0)
	v_mov_b32_e32 v0, 0x2000
	global_load_dword v0, v0, s[4:5] offset:1024 sc1
	s_add_u32 s14, s4, 0x2400
	s_addc_u32 s15, s5, 0
	s_waitcnt vmcnt(0)
	v_cmp_eq_u32_e32 vcc, v0, v1
	s_and_saveexec_b64 s[8:9], vcc
	s_cbranch_execz .LBB0_1077
	s_add_u32 s10, s66, 0x4200
	s_addc_u32 s11, s67, 0
	s_mov_b32 s26, 1
	s_mov_b64 s[16:17], 0
	v_mov_b32_e32 v0, 0
	s_branch .LBB0_1068

; __device__ __forceinline__ unsigned xb_ld(unsigned* p)              { return __hip_atomic_load(p, __ATOMIC_RELAXED, __HIP_MEMORY_SCOPE_AGENT); }
; __device__ __forceinline__ unsigned xb_add(unsigned* p, unsigned v) { return __hip_atomic_fetch_add(p, v, __ATOMIC_RELAXED, __HIP_MEMORY_SCOPE_AGENT); }
; #define XB_SPIN(cond, bar) do { unsigned _sp = 0; while (cond) { __builtin_amdgcn_s_sleep(1); \
;     if ((++_sp & 255u) == 0u) { if (xb_ld(&(bar)[XB_TMO])) break; if (_sp > XB_SPIN_CAP) { atomicAdd(&(bar)[XB_TMO], 1u); break; } } } } while (0)
; __device__ __forceinline__ void xcd_barrier(const XcdBarrier& b) {
;     ...
;             const unsigned og = xb_add(&bar[XB_TOP], 1u);
;             const unsigned tg = og / nx;
;             if (og + 1u == (tg + 1u) * nx) xb_add(&bar[XB_TOPGEN], 1u);
;             else XB_SPIN(xb_ld(&bar[XB_TOPGEN]) == tg, bar);
.LBB0_1081:
	s_or_b64 exec, exec, s[8:9]
	v_cvt_f32_u32_e32 v3, v0
	s_waitcnt vmcnt(0)
	v_readfirstlane_b32 s6, v2
	s_add_u32 s8, s66, 0x7500
	s_addc_u32 s9, s67, 0
	s_mov_b64 s[10:11], -1
	v_mul_u32_u24_e32 v0, 4, v0
	s_nop 1
	v_add_u32_e32 v1, s6, v1
	v_add_u32_e32 v4, 1, v1
	v_mov_b32_e32 v2, 3
	v_cmp_ne_u32_e32 vcc, v4, v0
	v_mov_b64_e32 v[0:1], s[8:9]
	s_cbranch_vccnz .Lxbh3_nl
	v_mov_b32_e32 v2, 1
	global_atomic_add v[0:1], v2, off
	v_subrev_co_u32_e32 v0, vcc, 0x1100, v0
	v_subbrev_co_u32_e32 v1, vcc, 0, v1, vcc
	global_atomic_add v[0:1], v2, off
	global_atomic_add v[0:1], v2, off offset:256
	global_atomic_add v[0:1], v2, off offset:512
	global_atomic_add v[0:1], v2, off offset:768
	global_atomic_add v[0:1], v2, off offset:1024
	global_atomic_add v[0:1], v2, off offset:1280
	global_atomic_add v[0:1], v2, off offset:1536
	global_atomic_add v[0:1], v2, off offset:1792
	global_atomic_add v[0:1], v2, off offset:2048
	global_atomic_add v[0:1], v2, off offset:2304
	global_atomic_add v[0:1], v2, off offset:2560
	global_atomic_add v[0:1], v2, off offset:2816
	global_atomic_add v[0:1], v2, off offset:3072
	global_atomic_add v[0:1], v2, off offset:3328
	global_atomic_add v[0:1], v2, off offset:3584
	global_atomic_add v[0:1], v2, off offset:3840
	s_mov_b64 s[6:7], exec
	s_branch .LBB0_1098

; __device__ __forceinline__ unsigned xb_ld(unsigned* p)              { return __hip_atomic_load(p, __ATOMIC_RELAXED, __HIP_MEMORY_SCOPE_AGENT); }
; __device__ __forceinline__ unsigned xb_add(unsigned* p, unsigned v) { return __hip_atomic_fetch_add(p, v, __ATOMIC_RELAXED, __HIP_MEMORY_SCOPE_AGENT); }
; #define XB_SPIN(cond, bar) do { unsigned _sp = 0; while (cond) { __builtin_amdgcn_s_sleep(1); \
;     if ((++_sp & 255u) == 0u) { if (xb_ld(&(bar)[XB_TMO])) break; if (_sp > XB_SPIN_CAP) { atomicAdd(&(bar)[XB_TMO], 1u); break; } } } } while (0)
; __device__ __forceinline__ void xcd_barrier(const XcdBarrier& b) {
;     ...
;         unsigned nloc = b.st[0], nx = b.st[1];
;         if (nloc == 0u) { xcd_barrier_complete(bar, b.x, nloc, nx); b.st[0] = nloc; b.st[1] = nx; }
;         const unsigned old = xb_add(&bar[XB_XSUB(b.x)], 1u);
;         const unsigned gen = old / nloc;
;         if (old + 1u == (gen + 1u) * nloc) {
;     ...
;             XB_SPIN(xb_ld(&bar[XB_XGEN(b.x)]) == gen, bar);
.LBB0_1244:
	s_or_b64 exec, exec, s[10:11]
	v_cvt_f32_u32_e32 v4, v2
	s_waitcnt vmcnt(0)
	buffer_inv sc1
	v_readfirstlane_b32 s8, v3
	v_mul_u32_u24_e32 v2, 5, v2
	s_nop 1
	v_add_u32_e32 v5, s8, v1
	v_add_u32_e32 v3, 1, v5
	v_mov_b32_e32 v1, 4
	v_cmp_ne_u32_e32 vcc, v3, v2
	s_and_saveexec_b64 s[8:9], vcc
	s_xor_b64 s[8:9], exec, s[8:9]
	s_cbranch_execz .LBB0_1258
	s_waitcnt lgkmcnt(0)
	v_mov_b32_e32 v0, 0x2000
	global_load_dword v0, v0, s[6:7] offset:1024 sc1
	s_add_u32 s14, s6, 0x2400
	s_addc_u32 s15, s7, 0
	s_waitcnt vmcnt(0)
	v_cmp_eq_u32_e32 vcc, v0, v1
	s_and_saveexec_b64 s[10:11], vcc
	s_cbranch_execz .LBB0_1257
	s_add_u32 s12, s66, 0x4200
	s_addc_u32 s13, s67, 0
	s_mov_b32 s26, 1
	s_mov_b64 s[16:17], 0
	v_mov_b32_e32 v0, 0
	s_branch .LBB0_1248

; __device__ __forceinline__ unsigned xb_ld(unsigned* p)              { return __hip_atomic_load(p, __ATOMIC_RELAXED, __HIP_MEMORY_SCOPE_AGENT); }
; __device__ __forceinline__ unsigned xb_add(unsigned* p, unsigned v) { return __hip_atomic_fetch_add(p, v, __ATOMIC_RELAXED, __HIP_MEMORY_SCOPE_AGENT); }
; #define XB_SPIN(cond, bar) do { unsigned _sp = 0; while (cond) { __builtin_amdgcn_s_sleep(1); \
;     if ((++_sp & 255u) == 0u) { if (xb_ld(&(bar)[XB_TMO])) break; if (_sp > XB_SPIN_CAP) { atomicAdd(&(bar)[XB_TMO], 1u); break; } } } } while (0)
; __device__ __forceinline__ void xcd_barrier(const XcdBarrier& b) {
;     ...
;             const unsigned og = xb_add(&bar[XB_TOP], 1u);
;             const unsigned tg = og / nx;
;             if (og + 1u == (tg + 1u) * nx) xb_add(&bar[XB_TOPGEN], 1u);
;             else XB_SPIN(xb_ld(&bar[XB_TOPGEN]) == tg, bar);
.LBB0_1261:
	s_or_b64 exec, exec, s[10:11]
	v_cvt_f32_u32_e32 v3, v0
	s_waitcnt vmcnt(0)
	v_readfirstlane_b32 s8, v2
	s_add_u32 s10, s66, 0x7500
	s_addc_u32 s11, s67, 0
	s_mov_b64 s[12:13], -1
	v_mul_u32_u24_e32 v0, 5, v0
	s_nop 1
	v_add_u32_e32 v1, s8, v1
	v_add_u32_e32 v4, 1, v1
	v_mov_b32_e32 v2, 4
	v_cmp_ne_u32_e32 vcc, v4, v0
	v_mov_b64_e32 v[0:1], s[10:11]
	s_cbranch_vccnz .Lxbh4_nl
	v_mov_b32_e32 v2, 1
	global_atomic_add v[0:1], v2, off
	v_subrev_co_u32_e32 v0, vcc, 0x1100, v0
	v_subbrev_co_u32_e32 v1, vcc, 0, v1, vcc
	global_atomic_add v[0:1], v2, off
	global_atomic_add v[0:1], v2, off offset:256
	global_atomic_add v[0:1], v2, off offset:512
	global_atomic_add v[0:1], v2, off offset:768
	global_atomic_add v[0:1], v2, off offset:1024
	global_atomic_add v[0:1], v2, off offset:1280
	global_atomic_add v[0:1], v2, off offset:1536
	global_atomic_add v[0:1], v2, off offset:1792
	global_atomic_add v[0:1], v2, off offset:2048
	global_atomic_add v[0:1], v2, off offset:2304
	global_atomic_add v[0:1], v2, off offset:2560
	global_atomic_add v[0:1], v2, off offset:2816
	global_atomic_add v[0:1], v2, off offset:3072
	global_atomic_add v[0:1], v2, off offset:3328
	global_atomic_add v[0:1], v2, off offset:3584
	global_atomic_add v[0:1], v2, off offset:3840
	s_mov_b64 s[8:9], exec
	s_branch .LBB0_1278

; __device__ __forceinline__ unsigned xb_ld(unsigned* p)              { return __hip_atomic_load(p, __ATOMIC_RELAXED, __HIP_MEMORY_SCOPE_AGENT); }
; __device__ __forceinline__ unsigned xb_add(unsigned* p, unsigned v) { return __hip_atomic_fetch_add(p, v, __ATOMIC_RELAXED, __HIP_MEMORY_SCOPE_AGENT); }
; #define XB_SPIN(cond, bar) do { unsigned _sp = 0; while (cond) { __builtin_amdgcn_s_sleep(1); \
;     if ((++_sp & 255u) == 0u) { if (xb_ld(&(bar)[XB_TMO])) break; if (_sp > XB_SPIN_CAP) { atomicAdd(&(bar)[XB_TMO], 1u); break; } } } } while (0)
; __device__ __forceinline__ void xcd_barrier(const XcdBarrier& b) {
;     ...
;         unsigned nloc = b.st[0], nx = b.st[1];
;         if (nloc == 0u) { xcd_barrier_complete(bar, b.x, nloc, nx); b.st[0] = nloc; b.st[1] = nx; }
;         const unsigned old = xb_add(&bar[XB_XSUB(b.x)], 1u);
;         const unsigned gen = old / nloc;
;         if (old + 1u == (gen + 1u) * nloc) {
;     ...
;             XB_SPIN(xb_ld(&bar[XB_XGEN(b.x)]) == gen, bar);
.LBB0_1301:
	s_or_b64 exec, exec, s[8:9]
	v_cvt_f32_u32_e32 v4, v2
	s_waitcnt vmcnt(0)
	buffer_inv sc1
	v_readfirstlane_b32 s6, v3
	v_mul_u32_u24_e32 v2, 6, v2
	s_nop 1
	v_add_u32_e32 v5, s6, v1
	v_add_u32_e32 v3, 1, v5
	v_mov_b32_e32 v1, 5
	v_cmp_ne_u32_e32 vcc, v3, v2
	s_and_saveexec_b64 s[6:7], vcc
	s_xor_b64 s[6:7], exec, s[6:7]
	s_cbranch_execz .LBB0_1315
	s_waitcnt lgkmcnt(0)
	v_mov_b32_e32 v0, 0x2000
	global_load_dword v0, v0, s[4:5] offset:1024 sc1
	s_add_u32 s12, s4, 0x2400
	s_addc_u32 s13, s5, 0
	s_waitcnt vmcnt(0)
	v_cmp_eq_u32_e32 vcc, v0, v1
	s_and_saveexec_b64 s[8:9], vcc
	s_cbranch_execz .LBB0_1314
	s_add_u32 s10, s66, 0x4200
	s_addc_u32 s11, s67, 0
	s_mov_b32 s24, 1
	s_mov_b64 s[14:15], 0
	v_mov_b32_e32 v0, 0
	s_branch .LBB0_1305

; __device__ __forceinline__ unsigned xb_ld(unsigned* p)              { return __hip_atomic_load(p, __ATOMIC_RELAXED, __HIP_MEMORY_SCOPE_AGENT); }
; __device__ __forceinline__ unsigned xb_add(unsigned* p, unsigned v) { return __hip_atomic_fetch_add(p, v, __ATOMIC_RELAXED, __HIP_MEMORY_SCOPE_AGENT); }
; #define XB_SPIN(cond, bar) do { unsigned _sp = 0; while (cond) { __builtin_amdgcn_s_sleep(1); \
;     if ((++_sp & 255u) == 0u) { if (xb_ld(&(bar)[XB_TMO])) break; if (_sp > XB_SPIN_CAP) { atomicAdd(&(bar)[XB_TMO], 1u); break; } } } } while (0)
; __device__ __forceinline__ void xcd_barrier(const XcdBarrier& b) {
;     ...
;         if (old + 1u == (gen + 1u) * nloc) {
;             __builtin_amdgcn_fence(__ATOMIC_RELEASE, "agent");
;             asm volatile("s_waitcnt vmcnt(0)" ::: "memory");
;             const unsigned og = xb_add(&bar[XB_TOP], 1u);
;             const unsigned tg = og / nx;
;             if (og + 1u == (tg + 1u) * nx) xb_add(&bar[XB_TOPGEN], 1u);
;             else XB_SPIN(xb_ld(&bar[XB_TOPGEN]) == tg, bar);
;             __builtin_amdgcn_fence(__ATOMIC_ACQUIRE, "agent");
;             xb_add(&bar[XB_XGEN(b.x)], 1u);
.LBB0_1318:
	s_or_b64 exec, exec, s[8:9]
	v_cvt_f32_u32_e32 v3, v0
	s_waitcnt vmcnt(0)
	v_readfirstlane_b32 s6, v2
	s_add_u32 s8, s66, 0x7500
	s_addc_u32 s9, s67, 0
	s_mov_b64 s[10:11], -1
	v_mul_u32_u24_e32 v0, 6, v0
	s_nop 1
	v_add_u32_e32 v1, s6, v1
	v_add_u32_e32 v4, 1, v1
	v_mov_b32_e32 v2, 5
	v_cmp_ne_u32_e32 vcc, v4, v0
	v_mov_b64_e32 v[0:1], s[8:9]
	s_cbranch_vccnz .Lxbh5_nl
	v_mov_b32_e32 v2, 1
	global_atomic_add v[0:1], v2, off
	v_subrev_co_u32_e32 v0, vcc, 0x1100, v0
	v_subbrev_co_u32_e32 v1, vcc, 0, v1, vcc
	global_atomic_add v[0:1], v2, off
	global_atomic_add v[0:1], v2, off offset:256
	global_atomic_add v[0:1], v2, off offset:512
	global_atomic_add v[0:1], v2, off offset:768
	global_atomic_add v[0:1], v2, off offset:1024
	global_atomic_add v[0:1], v2, off offset:1280
	global_atomic_add v[0:1], v2, off offset:1536
	global_atomic_add v[0:1], v2, off offset:1792
	global_atomic_add v[0:1], v2, off offset:2048
	global_atomic_add v[0:1], v2, off offset:2304
	global_atomic_add v[0:1], v2, off offset:2560
	global_atomic_add v[0:1], v2, off offset:2816
	global_atomic_add v[0:1], v2, off offset:3072
	global_atomic_add v[0:1], v2, off offset:3328
	global_atomic_add v[0:1], v2, off offset:3584
	global_atomic_add v[0:1], v2, off offset:3840
	s_mov_b64 s[6:7], exec
	s_branch .LBB0_1335

; __device__ __forceinline__ unsigned xb_ld(unsigned* p)              { return __hip_atomic_load(p, __ATOMIC_RELAXED, __HIP_MEMORY_SCOPE_AGENT); }
; __device__ __forceinline__ unsigned xb_add(unsigned* p, unsigned v) { return __hip_atomic_fetch_add(p, v, __ATOMIC_RELAXED, __HIP_MEMORY_SCOPE_AGENT); }
; #define XB_SPIN(cond, bar) do { unsigned _sp = 0; while (cond) { __builtin_amdgcn_s_sleep(1); \
;     if ((++_sp & 255u) == 0u) { if (xb_ld(&(bar)[XB_TMO])) break; if (_sp > XB_SPIN_CAP) { atomicAdd(&(bar)[XB_TMO], 1u); break; } } } } while (0)
; __device__ __forceinline__ void xcd_barrier(const XcdBarrier& b) {
;     ...
;         unsigned nloc = b.st[0], nx = b.st[1];
;         if (nloc == 0u) { xcd_barrier_complete(bar, b.x, nloc, nx); b.st[0] = nloc; b.st[1] = nx; }
;         const unsigned old = xb_add(&bar[XB_XSUB(b.x)], 1u);
;         const unsigned gen = old / nloc;
;         if (old + 1u == (gen + 1u) * nloc) {
;             __builtin_amdgcn_fence(__ATOMIC_RELEASE, "agent");
;             asm volatile("s_waitcnt vmcnt(0)" ::: "memory");
;             const unsigned og = xb_add(&bar[XB_TOP], 1u);
;             const unsigned tg = og / nx;
;             if (og + 1u == (tg + 1u) * nx) xb_add(&bar[XB_TOPGEN], 1u);
;             else XB_SPIN(xb_ld(&bar[XB_TOPGEN]) == tg, bar);
;             __builtin_amdgcn_fence(__ATOMIC_ACQUIRE, "agent");
;             xb_add(&bar[XB_XGEN(b.x)], 1u);
;             asm volatile("s_waitcnt vmcnt(0)" ::: "memory");
;         } else {
;             XB_SPIN(xb_ld(&bar[XB_XGEN(b.x)]) == gen, bar);
;             __builtin_amdgcn_fence(__ATOMIC_ACQUIRE, "agent");
;             asm volatile("s_waitcnt vmcnt(0)" ::: "memory");
;         }
.LBB0_1363:
	s_or_b64 exec, exec, s[8:9]
	v_cvt_f32_u32_e32 v4, v2
	s_waitcnt vmcnt(0)
	buffer_inv sc1
	v_readfirstlane_b32 s6, v3
	v_mul_u32_u24_e32 v2, 7, v2
	s_nop 1
	v_add_u32_e32 v5, s6, v1
	v_add_u32_e32 v3, 1, v5
	v_mov_b32_e32 v1, 6
	v_cmp_ne_u32_e32 vcc, v3, v2
	s_and_saveexec_b64 s[6:7], vcc
	s_xor_b64 s[6:7], exec, s[6:7]
	s_cbranch_execz .LBB0_1377
	s_waitcnt lgkmcnt(0)
	v_mov_b32_e32 v0, 0x2000
	global_load_dword v0, v0, s[4:5] offset:1024 sc1
	s_add_u32 s12, s4, 0x2400
	s_addc_u32 s13, s5, 0
	s_waitcnt vmcnt(0)
	v_cmp_eq_u32_e32 vcc, v0, v1
	s_and_saveexec_b64 s[8:9], vcc
	s_cbranch_execz .LBB0_1376
	s_add_u32 s10, s66, 0x4200
	s_addc_u32 s11, s67, 0
	s_mov_b32 s24, 1
	s_mov_b64 s[14:15], 0
	v_mov_b32_e32 v0, 0
	s_branch .LBB0_1367

; __device__ __forceinline__ unsigned xb_ld(unsigned* p)              { return __hip_atomic_load(p, __ATOMIC_RELAXED, __HIP_MEMORY_SCOPE_AGENT); }
; __device__ __forceinline__ unsigned xb_add(unsigned* p, unsigned v) { return __hip_atomic_fetch_add(p, v, __ATOMIC_RELAXED, __HIP_MEMORY_SCOPE_AGENT); }
; #define XB_SPIN(cond, bar) do { unsigned _sp = 0; while (cond) { __builtin_amdgcn_s_sleep(1); \
;     if ((++_sp & 255u) == 0u) { if (xb_ld(&(bar)[XB_TMO])) break; if (_sp > XB_SPIN_CAP) { atomicAdd(&(bar)[XB_TMO], 1u); break; } } } } while (0)
; __device__ __forceinline__ void xcd_barrier(const XcdBarrier& b) {
;     ...
;         if (old + 1u == (gen + 1u) * nloc) {
;             __builtin_amdgcn_fence(__ATOMIC_RELEASE, "agent");
;             asm volatile("s_waitcnt vmcnt(0)" ::: "memory");
;             const unsigned og = xb_add(&bar[XB_TOP], 1u);
;             const unsigned tg = og / nx;
;             if (og + 1u == (tg + 1u) * nx) xb_add(&bar[XB_TOPGEN], 1u);
;             else XB_SPIN(xb_ld(&bar[XB_TOPGEN]) == tg, bar);
;             __builtin_amdgcn_fence(__ATOMIC_ACQUIRE, "agent");
;             xb_add(&bar[XB_XGEN(b.x)], 1u);
.LBB0_1380:
	s_or_b64 exec, exec, s[8:9]
	v_cvt_f32_u32_e32 v3, v0
	s_waitcnt vmcnt(0)
	v_readfirstlane_b32 s6, v2
	s_add_u32 s8, s66, 0x7500
	s_addc_u32 s9, s67, 0
	s_mov_b64 s[10:11], -1
	v_mul_u32_u24_e32 v0, 7, v0
	s_nop 1
	v_add_u32_e32 v1, s6, v1
	v_add_u32_e32 v4, 1, v1
	v_mov_b32_e32 v2, 6
	v_cmp_ne_u32_e32 vcc, v4, v0
	v_mov_b64_e32 v[0:1], s[8:9]
	s_cbranch_vccnz .Lxbh6_nl
	v_mov_b32_e32 v2, 1
	global_atomic_add v[0:1], v2, off
	v_subrev_co_u32_e32 v0, vcc, 0x1100, v0
	v_subbrev_co_u32_e32 v1, vcc, 0, v1, vcc
	global_atomic_add v[0:1], v2, off
	global_atomic_add v[0:1], v2, off offset:256
	global_atomic_add v[0:1], v2, off offset:512
	global_atomic_add v[0:1], v2, off offset:768
	global_atomic_add v[0:1], v2, off offset:1024
	global_atomic_add v[0:1], v2, off offset:1280
	global_atomic_add v[0:1], v2, off offset:1536
	global_atomic_add v[0:1], v2, off offset:1792
	global_atomic_add v[0:1], v2, off offset:2048
	global_atomic_add v[0:1], v2, off offset:2304
	global_atomic_add v[0:1], v2, off offset:2560
	global_atomic_add v[0:1], v2, off offset:2816
	global_atomic_add v[0:1], v2, off offset:3072
	global_atomic_add v[0:1], v2, off offset:3328
	global_atomic_add v[0:1], v2, off offset:3584
	global_atomic_add v[0:1], v2, off offset:3840
	s_mov_b64 s[6:7], exec
	s_branch .LBB0_1397

; __device__ __forceinline__ unsigned xb_ld(unsigned* p)              { return __hip_atomic_load(p, __ATOMIC_RELAXED, __HIP_MEMORY_SCOPE_AGENT); }
; __device__ __forceinline__ unsigned xb_add(unsigned* p, unsigned v) { return __hip_atomic_fetch_add(p, v, __ATOMIC_RELAXED, __HIP_MEMORY_SCOPE_AGENT); }
; #define XB_SPIN(cond, bar) do { unsigned _sp = 0; while (cond) { __builtin_amdgcn_s_sleep(1); \
;     if ((++_sp & 255u) == 0u) { if (xb_ld(&(bar)[XB_TMO])) break; if (_sp > XB_SPIN_CAP) { atomicAdd(&(bar)[XB_TMO], 1u); break; } } } } while (0)
; __device__ __forceinline__ void xcd_barrier(const XcdBarrier& b) {
;     ...
;         unsigned nloc = b.st[0], nx = b.st[1];
;         if (nloc == 0u) { xcd_barrier_complete(bar, b.x, nloc, nx); b.st[0] = nloc; b.st[1] = nx; }
;         const unsigned old = xb_add(&bar[XB_XSUB(b.x)], 1u);
;         const unsigned gen = old / nloc;
;         if (old + 1u == (gen + 1u) * nloc) {
;             __builtin_amdgcn_fence(__ATOMIC_RELEASE, "agent");
;             asm volatile("s_waitcnt vmcnt(0)" ::: "memory");
;             const unsigned og = xb_add(&bar[XB_TOP], 1u);
;             const unsigned tg = og / nx;
;             if (og + 1u == (tg + 1u) * nx) xb_add(&bar[XB_TOPGEN], 1u);
;             else XB_SPIN(xb_ld(&bar[XB_TOPGEN]) == tg, bar);
;             __builtin_amdgcn_fence(__ATOMIC_ACQUIRE, "agent");
;             xb_add(&bar[XB_XGEN(b.x)], 1u);
;             asm volatile("s_waitcnt vmcnt(0)" ::: "memory");
;         } else {
;             XB_SPIN(xb_ld(&bar[XB_XGEN(b.x)]) == gen, bar);
;             __builtin_amdgcn_fence(__ATOMIC_ACQUIRE, "agent");
;             asm volatile("s_waitcnt vmcnt(0)" ::: "memory");
;         }
.LBB0_1563:
	s_or_b64 exec, exec, s[6:7]
	v_cvt_f32_u32_e32 v4, v2
	s_waitcnt vmcnt(0)
	buffer_inv sc1
	v_readfirstlane_b32 s4, v3
	v_mul_u32_u24_e32 v2, 8, v2
	s_nop 1
	v_add_u32_e32 v5, s4, v1
	v_add_u32_e32 v3, 1, v5
	v_mov_b32_e32 v1, 7
	v_cmp_ne_u32_e32 vcc, v3, v2
	s_and_saveexec_b64 s[4:5], vcc
	s_xor_b64 s[4:5], exec, s[4:5]
	s_cbranch_execz .LBB0_1577
	s_waitcnt lgkmcnt(0)
	v_mov_b32_e32 v0, 0x2000
	global_load_dword v0, v0, s[2:3] offset:1024 sc1
	s_add_u32 s10, s2, 0x2400
	s_addc_u32 s11, s3, 0
	s_waitcnt vmcnt(0)
	v_cmp_eq_u32_e32 vcc, v0, v1
	s_and_saveexec_b64 s[6:7], vcc
	s_cbranch_execz .LBB0_1576
	s_add_u32 s8, s66, 0x4200
	s_addc_u32 s9, s67, 0
	s_mov_b32 s22, 1
	s_mov_b64 s[12:13], 0
	v_mov_b32_e32 v0, 0
	s_branch .LBB0_1567

; __device__ __forceinline__ unsigned xb_ld(unsigned* p)              { return __hip_atomic_load(p, __ATOMIC_RELAXED, __HIP_MEMORY_SCOPE_AGENT); }
; __device__ __forceinline__ unsigned xb_add(unsigned* p, unsigned v) { return __hip_atomic_fetch_add(p, v, __ATOMIC_RELAXED, __HIP_MEMORY_SCOPE_AGENT); }
; #define XB_SPIN(cond, bar) do { unsigned _sp = 0; while (cond) { __builtin_amdgcn_s_sleep(1); \
;     if ((++_sp & 255u) == 0u) { if (xb_ld(&(bar)[XB_TMO])) break; if (_sp > XB_SPIN_CAP) { atomicAdd(&(bar)[XB_TMO], 1u); break; } } } } while (0)
; __device__ __forceinline__ void xcd_barrier(const XcdBarrier& b) {
;     ...
;         if (old + 1u == (gen + 1u) * nloc) {
;             __builtin_amdgcn_fence(__ATOMIC_RELEASE, "agent");
;             asm volatile("s_waitcnt vmcnt(0)" ::: "memory");
;             const unsigned og = xb_add(&bar[XB_TOP], 1u);
;             const unsigned tg = og / nx;
;             if (og + 1u == (tg + 1u) * nx) xb_add(&bar[XB_TOPGEN], 1u);
;             else XB_SPIN(xb_ld(&bar[XB_TOPGEN]) == tg, bar);
;             __builtin_amdgcn_fence(__ATOMIC_ACQUIRE, "agent");
;             xb_add(&bar[XB_XGEN(b.x)], 1u);
.LBB0_1580:
	s_or_b64 exec, exec, s[6:7]
	v_cvt_f32_u32_e32 v3, v0
	s_waitcnt vmcnt(0)
	v_readfirstlane_b32 s4, v2
	s_add_u32 s6, s66, 0x7500
	s_addc_u32 s7, s67, 0
	s_mov_b64 s[8:9], -1
	v_mul_u32_u24_e32 v0, 8, v0
	s_nop 1
	v_add_u32_e32 v1, s4, v1
	v_add_u32_e32 v4, 1, v1
	v_mov_b32_e32 v2, 7
	v_cmp_ne_u32_e32 vcc, v4, v0
	v_mov_b64_e32 v[0:1], s[6:7]
	s_cbranch_vccnz .Lxbh7_nl
	v_mov_b32_e32 v2, 1
	global_atomic_add v[0:1], v2, off
	v_subrev_co_u32_e32 v0, vcc, 0x1100, v0
	v_subbrev_co_u32_e32 v1, vcc, 0, v1, vcc
	global_atomic_add v[0:1], v2, off
	global_atomic_add v[0:1], v2, off offset:256
	global_atomic_add v[0:1], v2, off offset:512
	global_atomic_add v[0:1], v2, off offset:768
	global_atomic_add v[0:1], v2, off offset:1024
	global_atomic_add v[0:1], v2, off offset:1280
	global_atomic_add v[0:1], v2, off offset:1536
	global_atomic_add v[0:1], v2, off offset:1792
	global_atomic_add v[0:1], v2, off offset:2048
	global_atomic_add v[0:1], v2, off offset:2304
	global_atomic_add v[0:1], v2, off offset:2560
	global_atomic_add v[0:1], v2, off offset:2816
	global_atomic_add v[0:1], v2, off offset:3072
	global_atomic_add v[0:1], v2, off offset:3328
	global_atomic_add v[0:1], v2, off offset:3584
	global_atomic_add v[0:1], v2, off offset:3840
	s_mov_b64 s[4:5], exec
	s_branch .LBB0_1597

; __device__ __forceinline__ unsigned xb_ld(unsigned* p)              { return __hip_atomic_load(p, __ATOMIC_RELAXED, __HIP_MEMORY_SCOPE_AGENT); }
; __device__ __forceinline__ unsigned xb_add(unsigned* p, unsigned v) { return __hip_atomic_fetch_add(p, v, __ATOMIC_RELAXED, __HIP_MEMORY_SCOPE_AGENT); }
; #define XB_SPIN(cond, bar) do { unsigned _sp = 0; while (cond) { __builtin_amdgcn_s_sleep(1); \
;     if ((++_sp & 255u) == 0u) { if (xb_ld(&(bar)[XB_TMO])) break; if (_sp > XB_SPIN_CAP) { atomicAdd(&(bar)[XB_TMO], 1u); break; } } } } while (0)
; __device__ __forceinline__ void xcd_barrier_light(const XcdBarrier& b) {
;     ...
;         unsigned nloc = b.st[0], nx = b.st[1];
;         if (nloc == 0u) { xcd_barrier_complete(bar, b.x, nloc, nx); b.st[0] = nloc; b.st[1] = nx; }
;         const unsigned old = xb_add(&bar[XB_XSUB(b.x)], 1u);
;         const unsigned gen = old / nloc;
;         if (old + 1u == (gen + 1u) * nloc) {
;             asm volatile("s_waitcnt vmcnt(0)" ::: "memory");
;             const unsigned og = xb_add(&bar[XB_TOP], 1u);
;             const unsigned tg = og / nx;
;             if (og + 1u == (tg + 1u) * nx) xb_add(&bar[XB_TOPGEN], 1u);
;             else XB_SPIN(xb_ld(&bar[XB_TOPGEN]) == tg, bar);
;             xb_add(&bar[XB_XGEN(b.x)], 1u);
;             asm volatile("s_waitcnt vmcnt(0)" ::: "memory");
;         } else {
;             XB_SPIN(xb_ld(&bar[XB_XGEN(b.x)]) == gen, bar);
;             asm volatile("s_waitcnt vmcnt(0)" ::: "memory");
;         }
.LBB0_1704:
	s_or_b64 exec, exec, s[8:9]
	v_cvt_f32_u32_e32 v4, v2
	s_waitcnt vmcnt(0)
	v_readfirstlane_b32 s6, v3
	v_mul_u32_u24_e32 v2, 9, v2
	s_nop 1
	v_add_u32_e32 v5, s6, v1
	v_add_u32_e32 v3, 1, v5
	v_mov_b32_e32 v1, 8
	v_cmp_ne_u32_e32 vcc, v3, v2
	s_and_saveexec_b64 s[6:7], vcc
	s_xor_b64 s[6:7], exec, s[6:7]
	s_cbranch_execz .LBB0_1718
	s_waitcnt lgkmcnt(0)
	v_mov_b32_e32 v0, 0x2000
	global_load_dword v0, v0, s[4:5] offset:1024 sc1
	s_add_u32 s12, s4, 0x2400
	s_addc_u32 s13, s5, 0
	s_waitcnt vmcnt(0)
	v_cmp_eq_u32_e32 vcc, v0, v1
	s_and_saveexec_b64 s[8:9], vcc
	s_cbranch_execz .LBB0_1717
	s_add_u32 s10, s66, 0x4200
	s_addc_u32 s11, s67, 0
	s_mov_b32 s24, 1
	s_mov_b64 s[14:15], 0
	v_mov_b32_e32 v0, 0
	s_branch .LBB0_1708

; __device__ __forceinline__ unsigned xb_ld(unsigned* p)              { return __hip_atomic_load(p, __ATOMIC_RELAXED, __HIP_MEMORY_SCOPE_AGENT); }
; __device__ __forceinline__ unsigned xb_add(unsigned* p, unsigned v) { return __hip_atomic_fetch_add(p, v, __ATOMIC_RELAXED, __HIP_MEMORY_SCOPE_AGENT); }
; #define XB_SPIN(cond, bar) do { unsigned _sp = 0; while (cond) { __builtin_amdgcn_s_sleep(1); \
;     if ((++_sp & 255u) == 0u) { if (xb_ld(&(bar)[XB_TMO])) break; if (_sp > XB_SPIN_CAP) { atomicAdd(&(bar)[XB_TMO], 1u); break; } } } } while (0)
; __device__ __forceinline__ void xcd_barrier_light(const XcdBarrier& b) {
;     ...
;         if (old + 1u == (gen + 1u) * nloc) {
;             asm volatile("s_waitcnt vmcnt(0)" ::: "memory");
;             const unsigned og = xb_add(&bar[XB_TOP], 1u);
;             const unsigned tg = og / nx;
;             if (og + 1u == (tg + 1u) * nx) xb_add(&bar[XB_TOPGEN], 1u);
;             else XB_SPIN(xb_ld(&bar[XB_TOPGEN]) == tg, bar);
;             xb_add(&bar[XB_XGEN(b.x)], 1u);
.LBB0_1721:
	s_or_b64 exec, exec, s[6:7]
	s_waitcnt lgkmcnt(0)
	v_cvt_f32_u32_e32 v3, v0
	s_waitcnt vmcnt(0)
	v_readfirstlane_b32 s6, v2
	s_add_u32 s8, s66, 0x7500
	s_addc_u32 s9, s67, 0
	s_mov_b64 s[10:11], -1
	v_mul_u32_u24_e32 v0, 9, v0
	s_nop 1
	v_add_u32_e32 v1, s6, v1
	v_add_u32_e32 v4, 1, v1
	v_mov_b32_e32 v2, 8
	v_cmp_ne_u32_e32 vcc, v4, v0
	v_mov_b64_e32 v[0:1], s[8:9]
	s_cbranch_vccnz .Lxbh8_nl
	v_mov_b32_e32 v2, 1
	global_atomic_add v[0:1], v2, off
	v_subrev_co_u32_e32 v0, vcc, 0x1100, v0
	v_subbrev_co_u32_e32 v1, vcc, 0, v1, vcc
	global_atomic_add v[0:1], v2, off
	global_atomic_add v[0:1], v2, off offset:256
	global_atomic_add v[0:1], v2, off offset:512
	global_atomic_add v[0:1], v2, off offset:768
	global_atomic_add v[0:1], v2, off offset:1024
	global_atomic_add v[0:1], v2, off offset:1280
	global_atomic_add v[0:1], v2, off offset:1536
	global_atomic_add v[0:1], v2, off offset:1792
	global_atomic_add v[0:1], v2, off offset:2048
	global_atomic_add v[0:1], v2, off offset:2304
	global_atomic_add v[0:1], v2, off offset:2560
	global_atomic_add v[0:1], v2, off offset:2816
	global_atomic_add v[0:1], v2, off offset:3072
	global_atomic_add v[0:1], v2, off offset:3328
	global_atomic_add v[0:1], v2, off offset:3584
	global_atomic_add v[0:1], v2, off offset:3840
	s_mov_b64 s[6:7], exec
	s_branch .LBB0_1738

; __device__ __forceinline__ unsigned xb_ld(unsigned* p)              { return __hip_atomic_load(p, __ATOMIC_RELAXED, __HIP_MEMORY_SCOPE_AGENT); }
; __device__ __forceinline__ unsigned xb_add(unsigned* p, unsigned v) { return __hip_atomic_fetch_add(p, v, __ATOMIC_RELAXED, __HIP_MEMORY_SCOPE_AGENT); }
; #define XB_SPIN(cond, bar) do { unsigned _sp = 0; while (cond) { __builtin_amdgcn_s_sleep(1); \
;     if ((++_sp & 255u) == 0u) { if (xb_ld(&(bar)[XB_TMO])) break; if (_sp > XB_SPIN_CAP) { atomicAdd(&(bar)[XB_TMO], 1u); break; } } } } while (0)
; __device__ __forceinline__ void xcd_barrier(const XcdBarrier& b) {
;     ...
;         unsigned nloc = b.st[0], nx = b.st[1];
;         if (nloc == 0u) { xcd_barrier_complete(bar, b.x, nloc, nx); b.st[0] = nloc; b.st[1] = nx; }
;         const unsigned old = xb_add(&bar[XB_XSUB(b.x)], 1u);
;         const unsigned gen = old / nloc;
;         if (old + 1u == (gen + 1u) * nloc) {
;             __builtin_amdgcn_fence(__ATOMIC_RELEASE, "agent");
;             asm volatile("s_waitcnt vmcnt(0)" ::: "memory");
;             const unsigned og = xb_add(&bar[XB_TOP], 1u);
;             const unsigned tg = og / nx;
;             if (og + 1u == (tg + 1u) * nx) xb_add(&bar[XB_TOPGEN], 1u);
;             else XB_SPIN(xb_ld(&bar[XB_TOPGEN]) == tg, bar);
;             __builtin_amdgcn_fence(__ATOMIC_ACQUIRE, "agent");
;             xb_add(&bar[XB_XGEN(b.x)], 1u);
;             asm volatile("s_waitcnt vmcnt(0)" ::: "memory");
;         } else {
;             XB_SPIN(xb_ld(&bar[XB_XGEN(b.x)]) == gen, bar);
;             __builtin_amdgcn_fence(__ATOMIC_ACQUIRE, "agent");
;             asm volatile("s_waitcnt vmcnt(0)" ::: "memory");
;         }
.LBB0_1756:
	s_or_b64 exec, exec, s[6:7]
	v_cvt_f32_u32_e32 v4, v2
	s_waitcnt vmcnt(0)
	buffer_inv sc1
	v_readfirstlane_b32 s4, v3
	v_mul_u32_u24_e32 v2, 10, v2
	s_nop 1
	v_add_u32_e32 v5, s4, v1
	v_add_u32_e32 v3, 1, v5
	v_mov_b32_e32 v1, 9
	v_cmp_ne_u32_e32 vcc, v3, v2
	s_and_saveexec_b64 s[4:5], vcc
	s_xor_b64 s[4:5], exec, s[4:5]
	s_cbranch_execz .LBB0_1770
	s_waitcnt lgkmcnt(0)
	v_mov_b32_e32 v0, 0x2000
	global_load_dword v0, v0, s[2:3] offset:1024 sc1
	s_add_u32 s10, s2, 0x2400
	s_addc_u32 s11, s3, 0
	s_waitcnt vmcnt(0)
	v_cmp_eq_u32_e32 vcc, v0, v1
	s_and_saveexec_b64 s[6:7], vcc
	s_cbranch_execz .LBB0_1769
	s_add_u32 s8, s66, 0x4200
	s_addc_u32 s9, s67, 0
	s_mov_b32 s22, 1
	s_mov_b64 s[12:13], 0
	v_mov_b32_e32 v0, 0
	s_branch .LBB0_1760

; __device__ __forceinline__ unsigned xb_ld(unsigned* p)              { return __hip_atomic_load(p, __ATOMIC_RELAXED, __HIP_MEMORY_SCOPE_AGENT); }
; __device__ __forceinline__ unsigned xb_add(unsigned* p, unsigned v) { return __hip_atomic_fetch_add(p, v, __ATOMIC_RELAXED, __HIP_MEMORY_SCOPE_AGENT); }
; #define XB_SPIN(cond, bar) do { unsigned _sp = 0; while (cond) { __builtin_amdgcn_s_sleep(1); \
;     if ((++_sp & 255u) == 0u) { if (xb_ld(&(bar)[XB_TMO])) break; if (_sp > XB_SPIN_CAP) { atomicAdd(&(bar)[XB_TMO], 1u); break; } } } } while (0)
; __device__ __forceinline__ void xcd_barrier(const XcdBarrier& b) {
;     ...
;         if (old + 1u == (gen + 1u) * nloc) {
;             __builtin_amdgcn_fence(__ATOMIC_RELEASE, "agent");
;             asm volatile("s_waitcnt vmcnt(0)" ::: "memory");
;             const unsigned og = xb_add(&bar[XB_TOP], 1u);
;             const unsigned tg = og / nx;
;             if (og + 1u == (tg + 1u) * nx) xb_add(&bar[XB_TOPGEN], 1u);
;             else XB_SPIN(xb_ld(&bar[XB_TOPGEN]) == tg, bar);
;             __builtin_amdgcn_fence(__ATOMIC_ACQUIRE, "agent");
;             xb_add(&bar[XB_XGEN(b.x)], 1u);
.LBB0_1773:
	s_or_b64 exec, exec, s[6:7]
	v_cvt_f32_u32_e32 v3, v0
	s_waitcnt vmcnt(0)
	v_readfirstlane_b32 s4, v2
	s_add_u32 s6, s66, 0x7500
	s_addc_u32 s7, s67, 0
	s_mov_b64 s[8:9], -1
	v_mul_u32_u24_e32 v0, 10, v0
	s_nop 1
	v_add_u32_e32 v1, s4, v1
	v_add_u32_e32 v4, 1, v1
	v_mov_b32_e32 v2, 9
	v_cmp_ne_u32_e32 vcc, v4, v0
	v_mov_b64_e32 v[0:1], s[6:7]
	s_cbranch_vccnz .Lxbh9_nl
	v_mov_b32_e32 v2, 1
	global_atomic_add v[0:1], v2, off
	v_subrev_co_u32_e32 v0, vcc, 0x1100, v0
	v_subbrev_co_u32_e32 v1, vcc, 0, v1, vcc
	global_atomic_add v[0:1], v2, off
	global_atomic_add v[0:1], v2, off offset:256
	global_atomic_add v[0:1], v2, off offset:512
	global_atomic_add v[0:1], v2, off offset:768
	global_atomic_add v[0:1], v2, off offset:1024
	global_atomic_add v[0:1], v2, off offset:1280
	global_atomic_add v[0:1], v2, off offset:1536
	global_atomic_add v[0:1], v2, off offset:1792
	global_atomic_add v[0:1], v2, off offset:2048
	global_atomic_add v[0:1], v2, off offset:2304
	global_atomic_add v[0:1], v2, off offset:2560
	global_atomic_add v[0:1], v2, off offset:2816
	global_atomic_add v[0:1], v2, off offset:3072
	global_atomic_add v[0:1], v2, off offset:3328
	global_atomic_add v[0:1], v2, off offset:3584
	global_atomic_add v[0:1], v2, off offset:3840
	s_mov_b64 s[4:5], exec
	s_branch .LBB0_1790

; __device__ __forceinline__ unsigned xb_ld(unsigned* p)              { return __hip_atomic_load(p, __ATOMIC_RELAXED, __HIP_MEMORY_SCOPE_AGENT); }
; __device__ __forceinline__ unsigned xb_add(unsigned* p, unsigned v) { return __hip_atomic_fetch_add(p, v, __ATOMIC_RELAXED, __HIP_MEMORY_SCOPE_AGENT); }
; #define XB_SPIN(cond, bar) do { unsigned _sp = 0; while (cond) { __builtin_amdgcn_s_sleep(1); \
;     if ((++_sp & 255u) == 0u) { if (xb_ld(&(bar)[XB_TMO])) break; if (_sp > XB_SPIN_CAP) { atomicAdd(&(bar)[XB_TMO], 1u); break; } } } } while (0)
; __device__ __forceinline__ void xcd_barrier(const XcdBarrier& b) {
;     ...
;         unsigned nloc = b.st[0], nx = b.st[1];
;         if (nloc == 0u) { xcd_barrier_complete(bar, b.x, nloc, nx); b.st[0] = nloc; b.st[1] = nx; }
;         const unsigned old = xb_add(&bar[XB_XSUB(b.x)], 1u);
;         const unsigned gen = old / nloc;
;         if (old + 1u == (gen + 1u) * nloc) {
;             __builtin_amdgcn_fence(__ATOMIC_RELEASE, "agent");
;             asm volatile("s_waitcnt vmcnt(0)" ::: "memory");
;             const unsigned og = xb_add(&bar[XB_TOP], 1u);
;             const unsigned tg = og / nx;
;             if (og + 1u == (tg + 1u) * nx) xb_add(&bar[XB_TOPGEN], 1u);
;             else XB_SPIN(xb_ld(&bar[XB_TOPGEN]) == tg, bar);
;             __builtin_amdgcn_fence(__ATOMIC_ACQUIRE, "agent");
;             xb_add(&bar[XB_XGEN(b.x)], 1u);
;             asm volatile("s_waitcnt vmcnt(0)" ::: "memory");
;         } else {
;             XB_SPIN(xb_ld(&bar[XB_XGEN(b.x)]) == gen, bar);
;             __builtin_amdgcn_fence(__ATOMIC_ACQUIRE, "agent");
;             asm volatile("s_waitcnt vmcnt(0)" ::: "memory");
;         }
.LBB0_1830:
	s_or_b64 exec, exec, s[10:11]
	v_cvt_f32_u32_e32 v4, v2
	s_waitcnt vmcnt(0)
	buffer_inv sc1
	v_readfirstlane_b32 s8, v3
	v_mul_u32_u24_e32 v2, 11, v2
	s_nop 1
	v_add_u32_e32 v5, s8, v1
	v_add_u32_e32 v3, 1, v5
	v_mov_b32_e32 v1, 10
	v_cmp_ne_u32_e32 vcc, v3, v2
	s_and_saveexec_b64 s[8:9], vcc
	s_xor_b64 s[8:9], exec, s[8:9]
	s_cbranch_execz .LBB0_1844
	s_waitcnt lgkmcnt(0)
	v_mov_b32_e32 v0, 0x2000
	global_load_dword v0, v0, s[6:7] offset:1024 sc1
	s_add_u32 s14, s6, 0x2400
	s_addc_u32 s15, s7, 0
	s_waitcnt vmcnt(0)
	v_cmp_eq_u32_e32 vcc, v0, v1
	s_and_saveexec_b64 s[10:11], vcc
	s_cbranch_execz .LBB0_1843
	s_add_u32 s12, s66, 0x4200
	s_addc_u32 s13, s67, 0
	s_mov_b32 s26, 1
	s_mov_b64 s[16:17], 0
	v_mov_b32_e32 v0, 0
	s_branch .LBB0_1834

; __device__ __forceinline__ unsigned xb_ld(unsigned* p)              { return __hip_atomic_load(p, __ATOMIC_RELAXED, __HIP_MEMORY_SCOPE_AGENT); }
; __device__ __forceinline__ unsigned xb_add(unsigned* p, unsigned v) { return __hip_atomic_fetch_add(p, v, __ATOMIC_RELAXED, __HIP_MEMORY_SCOPE_AGENT); }
; #define XB_SPIN(cond, bar) do { unsigned _sp = 0; while (cond) { __builtin_amdgcn_s_sleep(1); \
;     if ((++_sp & 255u) == 0u) { if (xb_ld(&(bar)[XB_TMO])) break; if (_sp > XB_SPIN_CAP) { atomicAdd(&(bar)[XB_TMO], 1u); break; } } } } while (0)
; __device__ __forceinline__ void xcd_barrier(const XcdBarrier& b) {
;     ...
;         if (old + 1u == (gen + 1u) * nloc) {
;             __builtin_amdgcn_fence(__ATOMIC_RELEASE, "agent");
;             asm volatile("s_waitcnt vmcnt(0)" ::: "memory");
;             const unsigned og = xb_add(&bar[XB_TOP], 1u);
;             const unsigned tg = og / nx;
;             if (og + 1u == (tg + 1u) * nx) xb_add(&bar[XB_TOPGEN], 1u);
;             else XB_SPIN(xb_ld(&bar[XB_TOPGEN]) == tg, bar);
;             __builtin_amdgcn_fence(__ATOMIC_ACQUIRE, "agent");
;             xb_add(&bar[XB_XGEN(b.x)], 1u);
.LBB0_1847:
	s_or_b64 exec, exec, s[10:11]
	v_cvt_f32_u32_e32 v3, v0
	s_waitcnt vmcnt(0)
	v_readfirstlane_b32 s8, v2
	s_add_u32 s10, s66, 0x7500
	s_addc_u32 s11, s67, 0
	s_mov_b64 s[12:13], -1
	v_mul_u32_u24_e32 v0, 11, v0
	s_nop 1
	v_add_u32_e32 v1, s8, v1
	v_add_u32_e32 v4, 1, v1
	v_mov_b32_e32 v2, 10
	v_cmp_ne_u32_e32 vcc, v4, v0
	v_mov_b64_e32 v[0:1], s[10:11]
	s_cbranch_vccnz .Lxbh10_nl
	v_mov_b32_e32 v2, 1
	global_atomic_add v[0:1], v2, off
	v_subrev_co_u32_e32 v0, vcc, 0x1100, v0
	v_subbrev_co_u32_e32 v1, vcc, 0, v1, vcc
	global_atomic_add v[0:1], v2, off
	global_atomic_add v[0:1], v2, off offset:256
	global_atomic_add v[0:1], v2, off offset:512
	global_atomic_add v[0:1], v2, off offset:768
	global_atomic_add v[0:1], v2, off offset:1024
	global_atomic_add v[0:1], v2, off offset:1280
	global_atomic_add v[0:1], v2, off offset:1536
	global_atomic_add v[0:1], v2, off offset:1792
	global_atomic_add v[0:1], v2, off offset:2048
	global_atomic_add v[0:1], v2, off offset:2304
	global_atomic_add v[0:1], v2, off offset:2560
	global_atomic_add v[0:1], v2, off offset:2816
	global_atomic_add v[0:1], v2, off offset:3072
	global_atomic_add v[0:1], v2, off offset:3328
	global_atomic_add v[0:1], v2, off offset:3584
	global_atomic_add v[0:1], v2, off offset:3840
	s_mov_b64 s[8:9], exec
	s_branch .LBB0_1864

; __device__ __forceinline__ unsigned xb_ld(unsigned* p)              { return __hip_atomic_load(p, __ATOMIC_RELAXED, __HIP_MEMORY_SCOPE_AGENT); }
; __device__ __forceinline__ unsigned xb_add(unsigned* p, unsigned v) { return __hip_atomic_fetch_add(p, v, __ATOMIC_RELAXED, __HIP_MEMORY_SCOPE_AGENT); }
; #define XB_SPIN(cond, bar) do { unsigned _sp = 0; while (cond) { __builtin_amdgcn_s_sleep(1); \
;     if ((++_sp & 255u) == 0u) { if (xb_ld(&(bar)[XB_TMO])) break; if (_sp > XB_SPIN_CAP) { atomicAdd(&(bar)[XB_TMO], 1u); break; } } } } while (0)
; __device__ __forceinline__ void xcd_barrier_light(const XcdBarrier& b) {
;     ...
;         unsigned nloc = b.st[0], nx = b.st[1];
;         if (nloc == 0u) { xcd_barrier_complete(bar, b.x, nloc, nx); b.st[0] = nloc; b.st[1] = nx; }
;         const unsigned old = xb_add(&bar[XB_XSUB(b.x)], 1u);
;         const unsigned gen = old / nloc;
;         if (old + 1u == (gen + 1u) * nloc) {
;             asm volatile("s_waitcnt vmcnt(0)" ::: "memory");
;             const unsigned og = xb_add(&bar[XB_TOP], 1u);
;             const unsigned tg = og / nx;
;             if (og + 1u == (tg + 1u) * nx) xb_add(&bar[XB_TOPGEN], 1u);
;             else XB_SPIN(xb_ld(&bar[XB_TOPGEN]) == tg, bar);
;             xb_add(&bar[XB_XGEN(b.x)], 1u);
;             asm volatile("s_waitcnt vmcnt(0)" ::: "memory");
;         } else {
;             XB_SPIN(xb_ld(&bar[XB_XGEN(b.x)]) == gen, bar);
;             asm volatile("s_waitcnt vmcnt(0)" ::: "memory");
;         }
.LBB0_1975:
	s_or_b64 exec, exec, s[6:7]
	v_cvt_f32_u32_e32 v64, v2
	s_waitcnt vmcnt(0)
	v_readfirstlane_b32 s4, v3
	v_mul_u32_u24_e32 v2, 12, v2
	s_nop 1
	v_add_u32_e32 v65, s4, v1
	v_add_u32_e32 v3, 1, v65
	v_mov_b32_e32 v1, 11
	v_cmp_ne_u32_e32 vcc, v3, v2
	s_and_saveexec_b64 s[4:5], vcc
	s_xor_b64 s[4:5], exec, s[4:5]
	s_cbranch_execz .LBB0_1989
	s_waitcnt lgkmcnt(0)
	v_mov_b32_e32 v0, 0x2000
	global_load_dword v0, v0, s[2:3] offset:1024 sc1
	s_add_u32 s10, s2, 0x2400
	s_addc_u32 s11, s3, 0
	s_waitcnt vmcnt(0)
	v_cmp_eq_u32_e32 vcc, v0, v1
	s_and_saveexec_b64 s[6:7], vcc
	s_cbranch_execz .LBB0_1988
	s_add_u32 s8, s66, 0x4200
	s_addc_u32 s9, s67, 0
	s_mov_b32 s22, 1
	s_mov_b64 s[12:13], 0
	v_mov_b32_e32 v0, 0
	s_branch .LBB0_1979

; __device__ __forceinline__ unsigned xb_ld(unsigned* p)              { return __hip_atomic_load(p, __ATOMIC_RELAXED, __HIP_MEMORY_SCOPE_AGENT); }
; __device__ __forceinline__ unsigned xb_add(unsigned* p, unsigned v) { return __hip_atomic_fetch_add(p, v, __ATOMIC_RELAXED, __HIP_MEMORY_SCOPE_AGENT); }
; #define XB_SPIN(cond, bar) do { unsigned _sp = 0; while (cond) { __builtin_amdgcn_s_sleep(1); \
;     if ((++_sp & 255u) == 0u) { if (xb_ld(&(bar)[XB_TMO])) break; if (_sp > XB_SPIN_CAP) { atomicAdd(&(bar)[XB_TMO], 1u); break; } } } } while (0)
; __device__ __forceinline__ void xcd_barrier_light(const XcdBarrier& b) {
;     ...
;         if (old + 1u == (gen + 1u) * nloc) {
;             asm volatile("s_waitcnt vmcnt(0)" ::: "memory");
;             const unsigned og = xb_add(&bar[XB_TOP], 1u);
;             const unsigned tg = og / nx;
;             if (og + 1u == (tg + 1u) * nx) xb_add(&bar[XB_TOPGEN], 1u);
;             else XB_SPIN(xb_ld(&bar[XB_TOPGEN]) == tg, bar);
;             xb_add(&bar[XB_XGEN(b.x)], 1u);
.LBB0_1992:
	s_or_b64 exec, exec, s[4:5]
	s_waitcnt lgkmcnt(0)
	v_cvt_f32_u32_e32 v3, v0
	s_waitcnt vmcnt(0)
	v_readfirstlane_b32 s4, v2
	s_add_u32 s6, s66, 0x7500
	s_addc_u32 s7, s67, 0
	s_mov_b64 s[8:9], -1
	v_mul_u32_u24_e32 v0, 12, v0
	s_nop 1
	v_add_u32_e32 v1, s4, v1
	v_add_u32_e32 v64, 1, v1
	v_mov_b32_e32 v2, 11
	v_cmp_ne_u32_e32 vcc, v64, v0
	v_mov_b64_e32 v[0:1], s[6:7]
	s_cbranch_vccnz .Lxbh11_nl
	v_mov_b32_e32 v2, 1
	global_atomic_add v[0:1], v2, off
	v_subrev_co_u32_e32 v0, vcc, 0x1100, v0
	v_subbrev_co_u32_e32 v1, vcc, 0, v1, vcc
	global_atomic_add v[0:1], v2, off
	global_atomic_add v[0:1], v2, off offset:256
	global_atomic_add v[0:1], v2, off offset:512
	global_atomic_add v[0:1], v2, off offset:768
	global_atomic_add v[0:1], v2, off offset:1024
	global_atomic_add v[0:1], v2, off offset:1280
	global_atomic_add v[0:1], v2, off offset:1536
	global_atomic_add v[0:1], v2, off offset:1792
	global_atomic_add v[0:1], v2, off offset:2048
	global_atomic_add v[0:1], v2, off offset:2304
	global_atomic_add v[0:1], v2, off offset:2560
	global_atomic_add v[0:1], v2, off offset:2816
	global_atomic_add v[0:1], v2, off offset:3072
	global_atomic_add v[0:1], v2, off offset:3328
	global_atomic_add v[0:1], v2, off offset:3584
	global_atomic_add v[0:1], v2, off offset:3840
	s_mov_b64 s[4:5], exec
	s_branch .LBB0_2009
